# scan prologue: the loader lanes also touch the r/k/v and lora lines of the next two chunks while the first chunk is fetched (later loads hit L2)
# speedup vs baseline: 1.0060x; 1.0060x over previous
; __device__ __forceinline__ void scan_issue(const ScanPtrs& Q, int J, int ci, int ltid, LStage& L, int toff) {
;     ...
;     const int tt = (ltid >> 4) + toff, c = (ltid & 15) * 4;
;     if (tt < jb.nsteps) {
;         const int tok = jb.tok0 + tt; const int tseq = jb.is_s ? tt : ci * SC_CH + tt;
;         const int gc = jb.h * 64 + c;
;         const bf16_t* zr = Q.z + (size_t)tok * DIN + gc;
;         L.r = *(const u32x2*)zr; L.k = *(const u32x2*)(zr + 512); L.v = *(const u32x2*)(zr + 1024);
;         if (tseq > 0) { L.rp = *(const u32x2*)(zr - DIN); L.kp = *(const u32x2*)(zr - DIN + 512); L.vp = *(const u32x2*)(zr - DIN + 1024); }
;         else if (jb.is_s) { const float* sp = Q.st_shift + (size_t)jb.seq * DSH + gc; L.fr = *(const f32x4*)sp; L.fk = *(const f32x4*)(sp + 512); L.fv = *(const f32x4*)(sp + 1024); }
.LBB0_412:
	v_cmp_gt_i32_e32 vcc, s76, v1
	s_and_saveexec_b64 s[68:69], vcc
	s_cbranch_execz .LBB0_411
	v_cmp_lt_i32_e64 s[14:15], s75, v1
	v_cmp_gt_i32_e64 s[16:17], s77, v1
	v_lshlrev_b32_e32 v102, 5, v0
	s_and_saveexec_b64 s[8:9], s[16:17]
	s_xor_b64 s[18:19], exec, s[8:9]
	v_ashrrev_i32_e32 v21, 5, v1
	v_lshl_add_u32 v18, v21, 11, v102
	s_or_saveexec_b64 s[18:19], s[18:19]
	v_mov_b32_e32 v20, 32
	v_add_u32_e32 v25, 0xffffff00, v1
	s_xor_b64 exec, exec, s[18:19]
	v_lshrrev_b32_e32 v21, 5, v25
	v_lshl_add_u32 v18, v21, 3, v101
	v_mov_b32_e32 v20, 8
	s_or_b64 exec, exec, s[18:19]
	v_cmp_lt_u32_e32 vcc, v92, v20
	v_lshlrev_b32_e32 v20, 4, v1
	v_cndmask_b32_e64 v24, v102, 0, s[14:15]
	v_and_or_b32 v26, v20, s78, v89
	s_and_saveexec_b64 s[18:19], vcc
	s_cbranch_execz .LBB0_427
	v_add_u32_e32 v20, v18, v92
	v_mov_b64_e32 v[22:23], s[24:25]
	v_mad_i64_i32 v[22:23], s[8:9], v20, s79, v[22:23]
	v_lshlrev_b32_e32 v18, 1, v26
	v_lshl_add_u64 v[22:23], v[22:23], 0, v[18:19]
	s_mov_b64 s[100:101], 0x44000
	v_lshl_add_u64 v[232:233], v[22:23], 0, s[100:101]
	global_load_dword v234, v[232:233], off
	global_load_dword v235, v[232:233], off offset:1024
	global_load_dword v236, v[232:233], off offset:2048
	v_lshl_add_u64 v[232:233], v[232:233], 0, s[100:101]
	global_load_dword v237, v[232:233], off
	global_load_dword v238, v[232:233], off offset:1024
	global_load_dword v239, v[232:233], off offset:2048
	global_load_dwordx2 v[62:63], v[22:23], off
	global_load_dwordx2 v[70:71], v[22:23], off offset:1024
	global_load_dwordx2 v[72:73], v[22:23], off offset:2048
	v_cmp_le_i32_e32 vcc, v24, v93
	s_and_saveexec_b64 s[8:9], vcc
	s_xor_b64 s[20:21], exec, s[8:9]
	s_cbranch_execz .LBB0_422
	s_and_saveexec_b64 s[70:71], s[14:15]
	s_cbranch_execz .LBB0_421
	s_waitcnt vmcnt(7)
	v_mov_b64_e32 v[6:7], s[28:29]
	v_mad_i64_i32 v[6:7], s[8:9], v21, s80, v[6:7]
	v_lshlrev_b32_e32 v8, 2, v26
	v_mov_b32_e32 v9, v19
	s_waitcnt vmcnt(5)
	v_lshl_add_u64 v[14:15], v[6:7], 0, v[8:9]
	global_load_dwordx4 v[6:9], v[14:15], off
	global_load_dwordx4 v[10:13], v[14:15], off offset:2048
	v_add_co_u32_e32 v14, vcc, 0x1000, v14
	s_nop 1
	v_addc_co_u32_e32 v15, vcc, 0, v15, vcc
	global_load_dwordx4 v[14:17], v[14:15], off

; __device__ __forceinline__ void scan_issue(const ScanPtrs& Q, int J, int ci, int ltid, LStage& L, int toff) {
;     ...
;         if (tseq > 0) { L.rp = *(const u32x2*)(zr - DIN); L.kp = *(const u32x2*)(zr - DIN + 512); L.vp = *(const u32x2*)(zr - DIN + 1024); }
;         else if (jb.is_s) { const float* sp = Q.st_shift + (size_t)jb.seq * DSH + gc; L.fr = *(const f32x4*)sp; L.fk = *(const f32x4*)(sp + 512); L.fv = *(const f32x4*)(sp + 1024); }
;         L.sw = *(const u32x2*)(Q.sw + (size_t)tok * 512 + gc); L.sa = *(const u32x2*)(Q.sa + (size_t)tok * 512 + gc);
.LBB0_424:
	s_or_b64 exec, exec, s[20:21]
	v_ashrrev_i32_e32 v21, 31, v20
	v_lshlrev_b64 v[20:21], 10, v[20:21]
	v_lshl_add_u64 v[22:23], s[54:55], 0, v[20:21]
	v_lshl_add_u64 v[20:21], s[26:27], 0, v[20:21]
	v_lshl_add_u64 v[22:23], v[22:23], 0, v[18:19]
	v_lshl_add_u64 v[20:21], v[20:21], 0, v[18:19]
	s_mov_b64 s[100:101], 0x8000
	v_lshl_add_u64 v[232:233], v[22:23], 0, s[100:101]
	v_lshl_add_u64 v[240:241], v[20:21], 0, s[100:101]
	global_load_dword v234, v[232:233], off
	global_load_dword v235, v[240:241], off
	v_lshl_add_u64 v[232:233], v[232:233], 0, s[100:101]
	v_lshl_add_u64 v[240:241], v[240:241], 0, s[100:101]
	global_load_dword v236, v[232:233], off
	global_load_dword v237, v[240:241], off
	global_load_dwordx2 v[82:83], v[22:23], off
	global_load_dwordx2 v[84:85], v[20:21], off
	s_or_b64 exec, exec, s[18:19]
	s_nor_b64 s[70:71], s[14:15], s[12:13]
	s_and_saveexec_b64 s[18:19], s[70:71]
	s_cbranch_execnz .LBB0_428

; __device__ __forceinline__ void scan_issue(const ScanPtrs& Q, int J, int ci, int ltid, LStage& L, int toff) {
;     ...
;     if (tt < jb.nsteps) {
;         const int tok = jb.tok0 + tt; const int tseq = jb.is_s ? tt : ci * SC_CH + tt;
;         const int gc = jb.h * 64 + c;
;         const bf16_t* zr = Q.z + (size_t)tok * DIN + gc;
;         L.r = *(const u32x2*)zr; L.k = *(const u32x2*)(zr + 512); L.v = *(const u32x2*)(zr + 1024);
;         if (tseq > 0) { L.rp = *(const u32x2*)(zr - DIN); L.kp = *(const u32x2*)(zr - DIN + 512); L.vp = *(const u32x2*)(zr - DIN + 1024); }
;         else if (jb.is_s) { const float* sp = Q.st_shift + (size_t)jb.seq * DSH + gc; L.fr = *(const f32x4*)sp; L.fk = *(const f32x4*)(sp + 512); L.fv = *(const f32x4*)(sp + 1024); }
;         L.sw = *(const u32x2*)(Q.sw + (size_t)tok * 512 + gc); L.sa = *(const u32x2*)(Q.sa + (size_t)tok * 512 + gc);
.LBB0_428:
	v_lshlrev_b32_e32 v18, 6, v1
	v_and_b32_e32 v18, 0xfffff800, v18
	v_add_u32_e32 v18, v18, v102
	v_or_b32_e32 v20, v18, v88
	v_mov_b64_e32 v[22:23], s[24:25]
	v_mad_i64_i32 v[22:23], s[8:9], v20, s79, v[22:23]
	v_lshlrev_b32_e32 v18, 1, v26
	v_lshl_add_u64 v[22:23], v[22:23], 0, v[18:19]
	s_mov_b64 s[100:101], 0x44000
	v_lshl_add_u64 v[232:233], v[22:23], 0, s[100:101]
	global_load_dword v234, v[232:233], off
	global_load_dword v235, v[232:233], off offset:1024
	global_load_dword v236, v[232:233], off offset:2048
	v_lshl_add_u64 v[232:233], v[232:233], 0, s[100:101]
	global_load_dword v237, v[232:233], off
	global_load_dword v238, v[232:233], off offset:1024
	global_load_dword v239, v[232:233], off offset:2048
	global_load_dwordx2 v[56:57], v[22:23], off
	global_load_dwordx2 v[60:61], v[22:23], off offset:1024
	global_load_dwordx2 v[68:69], v[22:23], off offset:2048
	v_cmp_gt_i32_e32 vcc, v102, v94
	s_and_saveexec_b64 s[20:21], vcc
	s_cbranch_execz .LBB0_430
	v_add_co_u32_e32 v26, vcc, 0xffffe000, v22
	s_nop 1
	v_addc_co_u32_e32 v27, vcc, -1, v23, vcc
	v_add_co_u32_e32 v22, vcc, 0xfffff000, v22
	s_nop 1
	v_addc_co_u32_e32 v23, vcc, -1, v23, vcc
	global_load_dwordx2 v[54:55], v[26:27], off offset:-512
	global_load_dwordx2 v[58:59], v[22:23], off offset:-3584
	global_load_dwordx2 v[66:67], v[22:23], off offset:-2560
.LBB0_430:
	s_or_b64 exec, exec, s[20:21]
	v_ashrrev_i32_e32 v21, 31, v20
	v_lshlrev_b64 v[20:21], 10, v[20:21]
	v_lshl_add_u64 v[22:23], s[54:55], 0, v[20:21]
	v_lshl_add_u64 v[20:21], s[26:27], 0, v[20:21]
	v_lshl_add_u64 v[22:23], v[22:23], 0, v[18:19]
	v_lshl_add_u64 v[20:21], v[20:21], 0, v[18:19]
	s_mov_b64 s[100:101], 0x8000
	v_lshl_add_u64 v[232:233], v[22:23], 0, s[100:101]
	v_lshl_add_u64 v[240:241], v[20:21], 0, s[100:101]
	global_load_dword v234, v[232:233], off
	global_load_dword v235, v[240:241], off
	v_lshl_add_u64 v[232:233], v[232:233], 0, s[100:101]
	v_lshl_add_u64 v[240:241], v[240:241], 0, s[100:101]
	global_load_dword v236, v[232:233], off
	global_load_dword v237, v[240:241], off
	global_load_dwordx2 v[78:79], v[22:23], off
	global_load_dwordx2 v[80:81], v[20:21], off
	s_or_b64 exec, exec, s[18:19]
	s_and_saveexec_b64 s[8:9], s[16:17]
	s_xor_b64 s[16:17], exec, s[8:9]
	s_cbranch_execnz .LBB0_426

; __device__ __forceinline__ void scan_issue(const ScanPtrs& Q, int J, int ci, int ltid, LStage& L, int toff) {
;     ...
;     const int tt = (ltid >> 4) + toff, c = (ltid & 15) * 4;
;     if (tt < jb.nsteps) {
;         const int tok = jb.tok0 + tt; const int tseq = jb.is_s ? tt : ci * SC_CH + tt;
;         const int gc = jb.h * 64 + c;
;         const bf16_t* zr = Q.z + (size_t)tok * DIN + gc;
;         L.r = *(const u32x2*)zr; L.k = *(const u32x2*)(zr + 512); L.v = *(const u32x2*)(zr + 1024);
;         if (tseq > 0) { L.rp = *(const u32x2*)(zr - DIN); L.kp = *(const u32x2*)(zr - DIN + 512); L.vp = *(const u32x2*)(zr - DIN + 1024); }
;         else if (jb.is_s) { const float* sp = Q.st_shift + (size_t)jb.seq * DSH + gc; L.fr = *(const f32x4*)sp; L.fk = *(const f32x4*)(sp + 512); L.fv = *(const f32x4*)(sp + 1024); }
.LBB0_1553:
	v_cmp_gt_i32_e32 vcc, s73, v1
	s_and_saveexec_b64 s[64:65], vcc
	s_cbranch_execz .LBB0_1552
	v_cmp_lt_i32_e64 s[12:13], s72, v1
	v_cmp_gt_i32_e64 s[14:15], s74, v1
	v_lshlrev_b32_e32 v102, 5, v0
	s_and_saveexec_b64 s[16:17], s[14:15]
	s_xor_b64 s[16:17], exec, s[16:17]
	v_ashrrev_i32_e32 v21, 5, v1
	v_lshl_add_u32 v18, v21, 11, v102
	s_or_saveexec_b64 s[16:17], s[16:17]
	v_mov_b32_e32 v20, 32
	v_add_u32_e32 v25, 0xffffff00, v1
	s_xor_b64 exec, exec, s[16:17]
	v_lshrrev_b32_e32 v21, 5, v25
	v_lshl_add_u32 v18, v21, 3, v101
	v_mov_b32_e32 v20, 8
	s_or_b64 exec, exec, s[16:17]
	v_cmp_lt_u32_e32 vcc, v92, v20
	v_lshlrev_b32_e32 v20, 4, v1
	v_cndmask_b32_e64 v24, v102, 0, s[12:13]
	v_and_or_b32 v26, v20, s75, v89
	s_and_saveexec_b64 s[16:17], vcc
	s_cbranch_execz .LBB0_1568
	v_add_u32_e32 v20, v18, v92
	v_mov_b64_e32 v[22:23], s[22:23]
	v_mad_i64_i32 v[22:23], s[18:19], v20, s76, v[22:23]
	v_lshlrev_b32_e32 v18, 1, v26
	v_lshl_add_u64 v[22:23], v[22:23], 0, v[18:19]
	s_mov_b64 s[100:101], 0x44000
	v_lshl_add_u64 v[232:233], v[22:23], 0, s[100:101]
	global_load_dword v234, v[232:233], off
	global_load_dword v235, v[232:233], off offset:1024
	global_load_dword v236, v[232:233], off offset:2048
	v_lshl_add_u64 v[232:233], v[232:233], 0, s[100:101]
	global_load_dword v237, v[232:233], off
	global_load_dword v238, v[232:233], off offset:1024
	global_load_dword v239, v[232:233], off offset:2048
	global_load_dwordx2 v[62:63], v[22:23], off
	global_load_dwordx2 v[70:71], v[22:23], off offset:1024
	global_load_dwordx2 v[72:73], v[22:23], off offset:2048
	v_cmp_le_i32_e32 vcc, v24, v93
	s_and_saveexec_b64 s[18:19], vcc
	s_xor_b64 s[18:19], exec, s[18:19]
	s_cbranch_execz .LBB0_1563
	s_and_saveexec_b64 s[66:67], s[12:13]
	s_cbranch_execz .LBB0_1562
	s_waitcnt vmcnt(7)
	v_mov_b64_e32 v[6:7], s[56:57]
	v_mad_i64_i32 v[6:7], s[44:45], v21, s77, v[6:7]
	v_lshlrev_b32_e32 v8, 2, v26
	v_mov_b32_e32 v9, v19
	s_waitcnt vmcnt(5)
	v_lshl_add_u64 v[14:15], v[6:7], 0, v[8:9]
	global_load_dwordx4 v[6:9], v[14:15], off
	global_load_dwordx4 v[10:13], v[14:15], off offset:2048
	v_add_co_u32_e32 v14, vcc, 0x1000, v14
	s_nop 1
	v_addc_co_u32_e32 v15, vcc, 0, v15, vcc
	global_load_dwordx4 v[14:17], v[14:15], off

; __device__ __forceinline__ void scan_issue(const ScanPtrs& Q, int J, int ci, int ltid, LStage& L, int toff) {
;     ...
;         if (tseq > 0) { L.rp = *(const u32x2*)(zr - DIN); L.kp = *(const u32x2*)(zr - DIN + 512); L.vp = *(const u32x2*)(zr - DIN + 1024); }
;         else if (jb.is_s) { const float* sp = Q.st_shift + (size_t)jb.seq * DSH + gc; L.fr = *(const f32x4*)sp; L.fk = *(const f32x4*)(sp + 512); L.fv = *(const f32x4*)(sp + 1024); }
;         L.sw = *(const u32x2*)(Q.sw + (size_t)tok * 512 + gc); L.sa = *(const u32x2*)(Q.sa + (size_t)tok * 512 + gc);
.LBB0_1565:
	s_or_b64 exec, exec, s[18:19]
	v_ashrrev_i32_e32 v21, 31, v20
	v_lshlrev_b64 v[20:21], 10, v[20:21]
	v_lshl_add_u64 v[22:23], s[54:55], 0, v[20:21]
	v_lshl_add_u64 v[20:21], s[24:25], 0, v[20:21]
	v_lshl_add_u64 v[22:23], v[22:23], 0, v[18:19]
	v_lshl_add_u64 v[20:21], v[20:21], 0, v[18:19]
	s_mov_b64 s[100:101], 0x8000
	v_lshl_add_u64 v[232:233], v[22:23], 0, s[100:101]
	v_lshl_add_u64 v[240:241], v[20:21], 0, s[100:101]
	global_load_dword v234, v[232:233], off
	global_load_dword v235, v[240:241], off
	v_lshl_add_u64 v[232:233], v[232:233], 0, s[100:101]
	v_lshl_add_u64 v[240:241], v[240:241], 0, s[100:101]
	global_load_dword v236, v[232:233], off
	global_load_dword v237, v[240:241], off
	global_load_dwordx2 v[82:83], v[22:23], off
	global_load_dwordx2 v[84:85], v[20:21], off
	s_or_b64 exec, exec, s[16:17]
	s_nor_b64 s[66:67], s[12:13], s[8:9]
	s_and_saveexec_b64 s[16:17], s[66:67]
	s_cbranch_execnz .LBB0_1569

; __device__ __forceinline__ void scan_issue(const ScanPtrs& Q, int J, int ci, int ltid, LStage& L, int toff) {
;     ...
;     if (tt < jb.nsteps) {
;         const int tok = jb.tok0 + tt; const int tseq = jb.is_s ? tt : ci * SC_CH + tt;
;         const int gc = jb.h * 64 + c;
;         const bf16_t* zr = Q.z + (size_t)tok * DIN + gc;
;         L.r = *(const u32x2*)zr; L.k = *(const u32x2*)(zr + 512); L.v = *(const u32x2*)(zr + 1024);
;         if (tseq > 0) { L.rp = *(const u32x2*)(zr - DIN); L.kp = *(const u32x2*)(zr - DIN + 512); L.vp = *(const u32x2*)(zr - DIN + 1024); }
;         else if (jb.is_s) { const float* sp = Q.st_shift + (size_t)jb.seq * DSH + gc; L.fr = *(const f32x4*)sp; L.fk = *(const f32x4*)(sp + 512); L.fv = *(const f32x4*)(sp + 1024); }
;         L.sw = *(const u32x2*)(Q.sw + (size_t)tok * 512 + gc); L.sa = *(const u32x2*)(Q.sa + (size_t)tok * 512 + gc);
.LBB0_1569:
	v_lshlrev_b32_e32 v18, 6, v1
	v_and_b32_e32 v18, 0xfffff800, v18
	v_add_u32_e32 v18, v18, v102
	v_or_b32_e32 v20, v18, v88
	v_mov_b64_e32 v[22:23], s[22:23]
	v_mad_i64_i32 v[22:23], s[18:19], v20, s76, v[22:23]
	v_lshlrev_b32_e32 v18, 1, v26
	v_lshl_add_u64 v[22:23], v[22:23], 0, v[18:19]
	s_mov_b64 s[100:101], 0x44000
	v_lshl_add_u64 v[232:233], v[22:23], 0, s[100:101]
	global_load_dword v234, v[232:233], off
	global_load_dword v235, v[232:233], off offset:1024
	global_load_dword v236, v[232:233], off offset:2048
	v_lshl_add_u64 v[232:233], v[232:233], 0, s[100:101]
	global_load_dword v237, v[232:233], off
	global_load_dword v238, v[232:233], off offset:1024
	global_load_dword v239, v[232:233], off offset:2048
	global_load_dwordx2 v[56:57], v[22:23], off
	global_load_dwordx2 v[60:61], v[22:23], off offset:1024
	global_load_dwordx2 v[68:69], v[22:23], off offset:2048
	v_cmp_gt_i32_e32 vcc, v102, v94
	s_and_saveexec_b64 s[18:19], vcc
	s_cbranch_execz .LBB0_1571
	v_add_co_u32_e32 v26, vcc, 0xffffe000, v22
	s_nop 1
	v_addc_co_u32_e32 v27, vcc, -1, v23, vcc
	v_add_co_u32_e32 v22, vcc, 0xfffff000, v22
	s_nop 1
	v_addc_co_u32_e32 v23, vcc, -1, v23, vcc
	global_load_dwordx2 v[54:55], v[26:27], off offset:-512
	global_load_dwordx2 v[58:59], v[22:23], off offset:-3584
	global_load_dwordx2 v[66:67], v[22:23], off offset:-2560
.LBB0_1571:
	s_or_b64 exec, exec, s[18:19]
	v_ashrrev_i32_e32 v21, 31, v20
	v_lshlrev_b64 v[20:21], 10, v[20:21]
	v_lshl_add_u64 v[22:23], s[54:55], 0, v[20:21]
	v_lshl_add_u64 v[20:21], s[24:25], 0, v[20:21]
	v_lshl_add_u64 v[22:23], v[22:23], 0, v[18:19]
	v_lshl_add_u64 v[20:21], v[20:21], 0, v[18:19]
	s_mov_b64 s[100:101], 0x8000
	v_lshl_add_u64 v[232:233], v[22:23], 0, s[100:101]
	v_lshl_add_u64 v[240:241], v[20:21], 0, s[100:101]
	global_load_dword v234, v[232:233], off
	global_load_dword v235, v[240:241], off
	v_lshl_add_u64 v[232:233], v[232:233], 0, s[100:101]
	v_lshl_add_u64 v[240:241], v[240:241], 0, s[100:101]
	global_load_dword v236, v[232:233], off
	global_load_dword v237, v[240:241], off
	global_load_dwordx2 v[78:79], v[22:23], off
	global_load_dwordx2 v[80:81], v[20:21], off
	s_or_b64 exec, exec, s[16:17]
	s_and_saveexec_b64 s[16:17], s[14:15]
	s_xor_b64 s[14:15], exec, s[16:17]
	s_cbranch_execnz .LBB0_1567
